# v088 plus tile-boundary pipelining in the HGRN in-proj and GLU GEMMs (next tile's rstd partials prefetched before the epilogue, no store drain at the tile top)
# speedup vs baseline: 1.0063x; 1.0063x over previous
; #define GPTR(T, ptr) ((__attribute__((address_space(1))) T*)(ptr))
; __device__ __forceinline__ int ptid_(int wave) { int l_; asm volatile("v_mbcnt_lo_u32_b32 %0, -1, 0\n\tv_mbcnt_hi_u32_b32 %0, -1, %0" : "=v"(l_)); return (wave << 6) | l_; }
; #define STAGE_B(P, br, kt) do { const char* _gb = (const char*)(Bt + ((long)(br) * K + (long)(kt) * BK)); \
;     __builtin_amdgcn_global_load_lds((const unsigned*)(_gb + bofl0), (unsigned*)((char*)(P) + gtid_ * 16), 16, 0, 0); \
;     __builtin_amdgcn_global_load_lds((const unsigned*)(_gb + (long)K * 128 + bofl0), (unsigned*)((char*)(P) + gtid_ * 16 + 8192), 16, 0, 0); } while (0)
; #define WAIT_V(n) asm volatile("s_waitcnt vmcnt(" #n ")" ::: "memory")
; template <int EPI>
; __device__ __forceinline__ void gemm_tile(const GemmArgs& g, int brow, int bcol, int parity, bool first, bool nvalid, int nbrow, int nbcol) {
;     ...
;   int gtid_ = ptid_(g.tid);
;   const int wid = gtid_ >> 6, lane = gtid_ & 63, wr = wid >> 2, wc = wid & 3, fr = lane & 15, fq = lane >> 4;
;   unsigned aofl0, bofl0;
;   { int _r, _c; stage_rc(gtid_ * 16, _r, _c); aofl0 = (unsigned)(_r * lda + _c) * 2u; bofl0 = (unsigned)(_r * K + _c) * 2u; }
;   f32x4 acc[2][2][4][2] = {};
;   bf16x8 At[4][2], B0[2][2], B1[2][2];
;   const int nt = K / BK;
;   float* rstd_s = (float*)(smem + 153600) + (parity & 1) * 256;
;   if (first) {
;     WAIT_V(0);
;     __syncthreads();
;     STAGE_B(SB(0, 0), bcol, 0); STAGE_A(SA(0, 0), brow, 0);
;     STAGE_B(SB(0, 1), bcol + HALF, 0); STAGE_A(SA(0, 1), brow + HALF, 0);
;   }
;   f32x4 ra0, ra1, ra2, ra3;
;   if constexpr (EPI != EPI_RES) {
;     if (gtid_ < 256) {
;       const __attribute__((address_space(1))) f32x4* pp = GPTR(const f32x4, g.rowss + (long)(brow + gtid_) * 16);
;       ra0 = pp[0]; ra1 = pp[1]; ra2 = pp[2]; ra3 = pp[3];
;     }
;   }
.LBB0_77:
	s_mov_b64 s[100:101], s[14:15]
	v_mbcnt_lo_u32_b32 v132, -1, 0
	v_mbcnt_hi_u32_b32 v132, -1, v132
	s_ashr_i32 s0, s21, 31
	v_or_b32_e32 v138, s33, v132
	v_ashrrev_i32_e32 v0, 31, v138
	v_lshrrev_b32_e32 v0, 26, v0
	v_add_u32_e32 v0, v138, v0
	v_ashrrev_i32_e32 v18, 6, v0
	v_bfe_i32 v0, v138, 27, 1
	v_lshlrev_b32_e32 v142, 4, v138
	v_lshrrev_b32_e32 v0, 22, v0
	v_add_u32_e32 v0, v142, v0
	v_and_b32_e32 v0, 0xfffffc00, v0
	v_sub_u32_e32 v0, v142, v0
	s_waitcnt lgkmcnt(0)
	v_lshrrev_b32_e32 v2, 4, v0
	v_bitop3_b32 v0, v2, v0, 32 bitop3:0x6c
	v_ashrrev_i32_e32 v3, 31, v0
	s_lshr_b32 s0, s0, 26
	v_lshrrev_b32_e32 v3, 26, v3
	s_add_i32 s0, s21, s0
	v_add_u32_e32 v3, v0, v3
	s_and_b32 s1, s0, 0xffffffc0
	v_ashrrev_i32_e32 v19, 6, v3
	v_and_b32_e32 v3, 0xc0, v3
	s_sub_i32 s34, s21, s1
	s_lshl_b32 s0, s0, 5
	v_sub_u32_e32 v0, v0, v3
	s_and_b32 s2, s0, 0xfffff800
	s_lshl_b32 s0, s34, 8
	v_lshlrev_b32_e32 v2, 3, v18
	v_lshlrev_b32_e32 v4, 5, v18
	v_ashrrev_i16_sdwa v0, v220, sext(v0) dst_sel:DWORD dst_unused:UNUSED_PAD src0_sel:DWORD src1_sel:BYTE_0
	s_and_b32 s3, s0, 0x700
	s_lshl_b32 s0, s34, 5
	v_and_b32_e32 v2, 0x1ffff0, v2
	v_and_b32_e32 v4, 32, v4
	v_bfe_i32 v20, v0, 0, 16
	s_and_b32 s12, s0, 0xffffff00
	v_add_u32_e32 v0, v4, v20
	v_add_lshl_u32 v2, v19, v2, 11
	v_add_u32_e32 v137, 0, v142
	v_readlane_b32 s0, v254, 7
	s_or_b32 s38, s3, s2
	v_lshl_add_u32 v0, v0, 1, v2
	s_and_b64 vcc, exec, s[14:15]
	v_add_u32_e32 v136, 0x2000, v137
	v_add_u32_e32 v135, s0, v142
	v_add_u32_e32 v134, 0x4000, v137
	v_add_u32_e32 v133, 0x6000, v137
	s_cbranch_vccnz .LBB0_79
	s_ashr_i32 s13, s12, 31
	s_lshl_b64 s[0:1], s[12:13], 11
	s_add_u32 s0, s22, s0
	s_addc_u32 s1, s23, s1
	s_add_i32 s13, 0, 0x10000
	v_add_u32_e32 v4, s13, v142
	s_waitcnt vmcnt(0)
	s_nop 0
	v_readfirstlane_b32 s13, v4
	s_mov_b32 m0, s13
	v_add_u32_e32 v4, 0x2000, v4
	s_barrier
	v_lshl_add_u64 v[2:3], s[0:1], 0, v[0:1]
	global_load_lds_dwordx4 v0, s[0:1]
	v_readfirstlane_b32 s0, v4
	s_ashr_i32 s39, s38, 31
	s_mov_b64 s[18:19], 0x20000
	s_mov_b32 m0, s0
	s_lshl_b64 s[0:1], s[38:39], 11
	v_lshl_add_u64 v[2:3], v[2:3], 0, s[18:19]
	s_add_u32 s0, s80, s0
	v_readfirstlane_b32 s13, v137
	global_load_lds_dwordx4 v[2:3], off
	s_addc_u32 s1, s81, s1
	s_mov_b32 m0, s13
	v_lshl_add_u64 v[2:3], s[0:1], 0, v[0:1]
	global_load_lds_dwordx4 v0, s[0:1]
	v_readfirstlane_b32 s0, v136
	s_mov_b32 m0, s0
	s_or_b32 s0, s12, 0x80
	s_ashr_i32 s1, s0, 31
	s_lshl_b64 s[0:1], s[0:1], 11
	v_lshl_add_u64 v[2:3], v[2:3], 0, s[18:19]
	s_add_u32 s0, s22, s0
	v_readfirstlane_b32 s13, v135
	global_load_lds_dwordx4 v[2:3], off
	s_addc_u32 s1, s23, s1
	s_mov_b32 m0, s13
	v_add_u32_e32 v4, 0x2000, v135
	v_lshl_add_u64 v[2:3], s[0:1], 0, v[0:1]
	global_load_lds_dwordx4 v0, s[0:1]
	v_readfirstlane_b32 s0, v4
	s_mov_b32 m0, s0
	s_or_b32 s0, s38, 0x80
	s_ashr_i32 s1, s0, 31
	s_lshl_b64 s[0:1], s[0:1], 11
	v_lshl_add_u64 v[2:3], v[2:3], 0, s[18:19]
	s_add_u32 s0, s80, s0
	v_readfirstlane_b32 s13, v134
	global_load_lds_dwordx4 v[2:3], off
	s_addc_u32 s1, s81, s1
	s_mov_b32 m0, s13
	v_lshl_add_u64 v[2:3], s[0:1], 0, v[0:1]
	global_load_lds_dwordx4 v0, s[0:1]
	v_readfirstlane_b32 s0, v133
	v_lshl_add_u64 v[2:3], v[2:3], 0, s[18:19]
	s_mov_b32 m0, s0
	s_nop 0
	global_load_lds_dwordx4 v[2:3], off
.LBB0_79:
	s_movk_i32 s0, 0x100
	v_cmp_gt_i32_e64 s[0:1], s0, v138
	s_mov_b64 vcc, s[100:101]
	s_cbranch_vccnz .Lhp_A_1
	s_and_saveexec_b64 s[18:19], s[0:1]
	s_cbranch_execz .LBB0_81
	v_add_u32_e32 v2, s38, v138
	v_ashrrev_i32_e32 v3, 31, v2
	v_readlane_b32 s26, v254, 62
	v_lshlrev_b64 v[2:3], 6, v[2:3]
	v_readlane_b32 s27, v254, 63
	s_nop 1
	v_lshl_add_u64 v[14:15], s[26:27], 0, v[2:3]
	global_load_dwordx4 v[2:5], v[14:15], off offset:48
	global_load_dwordx4 v[6:9], v[14:15], off offset:32
	global_load_dwordx4 v[10:13], v[14:15], off offset:16
	s_nop 0
	global_load_dwordx4 v[14:17], v[14:15], off

; #define BAR __builtin_amdgcn_s_barrier()
; template <int EPI>
; __device__ __forceinline__ void gemm_tile(const GemmArgs& g, int brow, int bcol, int parity, bool first, bool nvalid, int nbrow, int nbcol) {
;     ...
;   if (wr == 1) BAR;
.Lhp_A_1:
	v_ashrrev_i32_e32 v21, 8, v138
	v_cmp_eq_u32_e32 vcc, 1, v21
	s_and_saveexec_b64 s[18:19], vcc
	s_cbranch_execz .LBB0_83
	s_barrier

; __device__ __forceinline__ float frsq(float x) { return __builtin_amdgcn_rsqf(x); }
; #define WAIT_V(n) asm volatile("s_waitcnt vmcnt(" #n ")" ::: "memory")
; #define BAR __builtin_amdgcn_s_barrier()
; template <int EPI>
; __device__ __forceinline__ void gemm_tile(const GemmArgs& g, int brow, int bcol, int parity, bool first, bool nvalid, int nbrow, int nbcol) {
;     ...
;   if (first) { WAIT_V(4); } else { WAIT_V(0); }
;   BAR;
;   if constexpr (EPI != EPI_RES) {
;     if (gtid_ < 256) {
;       float s = ((ra0[0] + ra0[1]) + (ra0[2] + ra0[3])) + ((ra1[0] + ra1[1]) + (ra1[2] + ra1[3])) + ((ra2[0] + ra2[1]) + (ra2[2] + ra2[3])) + ((ra3[0] + ra3[1]) + (ra3[2] + ra3[3]));
;       rstd_s[gtid_] = frsq(s * (1.0f / 1024.0f) + 1e-6f);
.LBB0_85:
	s_andn2_b64 vcc, exec, s[14:15]
	s_cbranch_vccnz .LBB0_87
	s_waitcnt vmcnt(16)
.LBB0_87:
	s_lshl_b32 s13, s24, 10
	s_and_b32 s13, s13, 0x400
	s_add_i32 s18, s13, 0
	s_add_i32 s18, s18, 0x25800
	s_barrier
	s_and_saveexec_b64 s[14:15], s[0:1]
	s_cbranch_execz .LBB0_89
	s_mov_b64 vcc, s[100:101]
	s_cbranch_vccz .Lhp_A_2
	v_mov_b32_e32 v2, v232
	v_mov_b32_e32 v3, v233
	v_mov_b32_e32 v4, v234
	v_mov_b32_e32 v5, v235
	v_mov_b32_e32 v6, v236
	v_mov_b32_e32 v7, v237
	v_mov_b32_e32 v8, v238
	v_mov_b32_e32 v9, v239
	v_mov_b32_e32 v10, v240
	v_mov_b32_e32 v11, v241
	v_mov_b32_e32 v12, v242
	v_mov_b32_e32 v13, v243
	v_mov_b32_e32 v14, v244
	v_mov_b32_e32 v15, v245
	v_mov_b32_e32 v16, v246
	v_mov_b32_e32 v17, v247
	s_branch .Lhp_A_3

; __device__ __forceinline__ float frsq(float x) { return __builtin_amdgcn_rsqf(x); }
; #define STAGE_B(P, br, kt) do { const char* _gb = (const char*)(Bt + ((long)(br) * K + (long)(kt) * BK)); \
;     __builtin_amdgcn_global_load_lds((const unsigned*)(_gb + bofl0), (unsigned*)((char*)(P) + gtid_ * 16), 16, 0, 0); \
;     __builtin_amdgcn_global_load_lds((const unsigned*)(_gb + (long)K * 128 + bofl0), (unsigned*)((char*)(P) + gtid_ * 16 + 8192), 16, 0, 0); } while (0)
; template <int EPI>
; __device__ __forceinline__ void gemm_tile(const GemmArgs& g, int brow, int bcol, int parity, bool first, bool nvalid, int nbrow, int nbcol) {
;     ...
;       float s = ((ra0[0] + ra0[1]) + (ra0[2] + ra0[3])) + ((ra1[0] + ra1[1]) + (ra1[2] + ra1[3])) + ((ra2[0] + ra2[1]) + (ra2[2] + ra2[3])) + ((ra3[0] + ra3[1]) + (ra3[2] + ra3[3]));
;       rstd_s[gtid_] = frsq(s * (1.0f / 1024.0f) + 1e-6f);
;     }
;   }
;   STAGE_B(SB(1, 0), bcol, 1); STAGE_A(SA(1, 0), brow, 1); STAGE_B(SB(1, 1), bcol + HALF, 1);
.Lhp_A_3:
	v_mov_b32_e32 v22, v15
	v_mov_b32_e32 v23, v16
	v_mov_b32_e32 v15, v17
	v_mov_b32_e32 v16, v11
	v_mov_b32_e32 v17, v12
	v_mov_b32_e32 v11, v13
	v_pk_add_f32 v[14:15], v[22:23], v[14:15]
	v_pk_add_f32 v[10:11], v[16:17], v[10:11]
	v_pk_add_f32 v[14:15], v[14:15], v[14:15] op_sel_hi:[0,1]
	v_pk_add_f32 v[10:11], v[10:11], v[10:11] op_sel_hi:[0,1]
	v_add_f32_e32 v7, v6, v7
	v_add_f32_e32 v9, v8, v9
	v_mov_b32_e32 v6, v2
	v_mov_b32_e32 v8, v3
	v_mov_b32_e32 v10, v4
	v_mov_b32_e32 v14, v5
	v_pk_add_f32 v[2:3], v[6:7], v[8:9]
	v_pk_add_f32 v[4:5], v[10:11], v[14:15]
	s_nop 0
	v_pk_add_f32 v[2:3], v[2:3], v[4:5]
	s_nop 0
	v_add_f32_e32 v2, v2, v3
	v_fmamk_f32 v2, v2, 0x3a800000, v201
	v_rsq_f32_e32 v2, v2
	v_lshl_add_u32 v3, v138, 2, s18
	ds_write_b32 v3, v2
.LBB0_89:
	s_or_b64 exec, exec, s[14:15]
	s_ashr_i32 s13, s12, 31
	s_lshl_b64 s[26:27], s[12:13], 11
	s_add_u32 s0, s22, s26
	v_readlane_b32 s13, v254, 8
	s_addc_u32 s1, s23, s27
	s_mov_b64 vcc, s[100:101]
	s_cbranch_vccz .Lhp_A_4
	s_waitcnt vmcnt(16)
	s_branch .Lhp_A_5

; #define STAGE_B(P, br, kt) do { const char* _gb = (const char*)(Bt + ((long)(br) * K + (long)(kt) * BK)); \
;     __builtin_amdgcn_global_load_lds((const unsigned*)(_gb + bofl0), (unsigned*)((char*)(P) + gtid_ * 16), 16, 0, 0); \
;     __builtin_amdgcn_global_load_lds((const unsigned*)(_gb + (long)K * 128 + bofl0), (unsigned*)((char*)(P) + gtid_ * 16 + 8192), 16, 0, 0); } while (0)
; #define WAIT_V(n) asm volatile("s_waitcnt vmcnt(" #n ")" ::: "memory")
; #define BAR __builtin_amdgcn_s_barrier()
; template <int EPI>
; __device__ __forceinline__ void gemm_tile(const GemmArgs& g, int brow, int bcol, int parity, bool first, bool nvalid, int nbrow, int nbcol) {
;     ...
;   f32x4 acc[2][2][4][2] = {};
;     ...
;   STAGE_B(SB(1, 0), bcol, 1); STAGE_A(SA(1, 0), brow, 1); STAGE_B(SB(1, 1), bcol + HALF, 1);
;   WAIT_V(6); BAR;
.Lhp_A_5:
	v_lshl_add_u64 v[2:3], s[0:1], 0, v[0:1]
	v_add_u32_e32 v150, s13, v142
	s_mov_b64 s[14:15], 0x80
	v_readfirstlane_b32 s0, v150
	v_add_u32_e32 v151, 0x2000, v150
	v_lshl_add_u64 v[4:5], v[2:3], 0, s[14:15]
	s_mov_b32 m0, s0
	v_readfirstlane_b32 s0, v151
	s_ashr_i32 s39, s38, 31
	global_load_lds_dwordx4 v[4:5], off
	s_mov_b32 m0, s0
	s_lshl_b64 s[0:1], s[38:39], 11
	s_mov_b64 s[36:37], 0x20080
	s_add_u32 s0, s80, s0
	v_lshl_add_u64 v[2:3], v[2:3], 0, s[36:37]
	s_addc_u32 s1, s81, s1
	v_add_u32_e32 v152, 0x8000, v137
	global_load_lds_dwordx4 v[2:3], off
	v_lshl_add_u64 v[2:3], s[0:1], 0, v[0:1]
	v_readfirstlane_b32 s0, v152
	v_add_u32_e32 v153, 0xa000, v137
	v_lshl_add_u64 v[4:5], v[2:3], 0, s[14:15]
	s_mov_b32 m0, s0
	v_readfirstlane_b32 s0, v153
	global_load_lds_dwordx4 v[4:5], off
	s_mov_b32 m0, s0
	s_or_b32 s0, s12, 0x80
	s_ashr_i32 s1, s0, 31
	s_lshl_b64 s[0:1], s[0:1], 11
	s_add_u32 s0, s22, s0
	v_lshl_add_u64 v[2:3], v[2:3], 0, s[36:37]
	s_addc_u32 s1, s23, s1
	global_load_lds_dwordx4 v[2:3], off
	v_lshl_add_u64 v[2:3], s[0:1], 0, v[0:1]
	v_readlane_b32 s1, v254, 9
	v_lshl_add_u64 v[4:5], v[2:3], 0, s[14:15]
	v_lshl_add_u64 v[2:3], v[2:3], 0, s[36:37]
	v_add_u32_e32 v155, s1, v142
	v_add_u32_e32 v156, 0x2000, v155
	v_readfirstlane_b32 s0, v155
	s_mov_b32 m0, s0
	v_readfirstlane_b32 s0, v156
	global_load_lds_dwordx4 v[4:5], off
	s_mov_b32 m0, s0
	v_and_b32_e32 v139, 15, v132
	global_load_lds_dwordx4 v[2:3], off
	v_lshlrev_b32_e32 v5, 2, v132
	v_and_b32_e32 v2, 48, v132
	v_lshlrev_b32_e32 v4, 6, v139
	v_and_b32_e32 v5, 32, v5
	v_bitop3_b32 v4, v4, v5, v2 bitop3:0x36
	v_readlane_b32 s0, v254, 7
	v_lshlrev_b32_e32 v11, 6, v132
	v_add_u32_e32 v9, s1, v4
	v_add_u32_e32 v7, s0, v4
	s_movk_i32 s0, 0x3c0
	v_and_or_b32 v2, v11, s0, v2
	s_add_i32 s0, s2, s3
	v_xad_u32 v5, v2, v5, 0
	v_lshlrev_b32_e32 v2, 14, v18
	s_ashr_i32 s1, s0, 31
	s_add_i32 s14, 0, 0x10000
	v_and_b32_e32 v2, 0xffff8000, v2
	s_lshl_b64 s[0:1], s[0:1], 11
	v_ashrrev_i32_e32 v140, 6, v138
	v_lshl_add_u32 v2, v19, 11, v2
	v_and_b32_e32 v14, 1, v18
	s_add_u32 s0, s10, s0
	v_and_b32_e32 v141, 3, v140
	s_mov_b64 vcc, s[100:101]
	s_cbranch_vccz .Lhp_A_6
	s_waitcnt vmcnt(22)
	s_branch .Lhp_A_7
.Lhp_A_6:
	s_waitcnt vmcnt(6)
.Lhp_A_7:
	v_lshlrev_b32_e32 v10, 13, v21
	v_lshl_or_b32 v2, v14, 6, v2
	s_addc_u32 s1, s11, s1
	v_lshlrev_b32_e32 v3, 12, v141
	v_add_u32_e32 v6, s14, v4
	v_add_u32_e32 v8, s13, v4
	v_add_u32_e32 v4, 0, v4
	v_or_b32_e32 v11, 0x800, v10
	v_or_b32_e32 v12, 0x1000, v10
	v_or_b32_e32 v13, 0x1800, v10
	v_lshl_add_u32 v130, v20, 1, v2
	s_add_u32 s12, s73, s26
	v_readlane_b32 s2, v255, 0
	v_mov_b32_e32 v2, 0
	v_lshlrev_b32_e32 v143, 6, v21
	v_mov_b32_e32 v131, v1
	s_addc_u32 s13, s2, s27
	s_mov_b32 s15, -2
	v_add_u32_e32 v157, v6, v3
	v_add_u32_e32 v147, v4, v10
	v_add_u32_e32 v146, v5, v11
	v_add_u32_e32 v145, v5, v12
	v_add_u32_e32 v144, v5, v13
	v_add_u32_e32 v154, v7, v3
	v_add_u32_e32 v149, v8, v3
	v_add_u32_e32 v148, v9, v3
	v_mov_b32_e32 v3, v2
	v_mov_b32_e32 v4, v2
	v_mov_b32_e32 v5, v2
	v_mov_b32_e32 v6, v2
	v_mov_b32_e32 v7, v2
	v_mov_b32_e32 v8, v2
	v_mov_b32_e32 v9, v2
	v_mov_b32_e32 v10, v2
	v_mov_b32_e32 v11, v2
	v_mov_b32_e32 v12, v2
	v_mov_b32_e32 v13, v2
	v_mov_b32_e32 v14, v2
	v_mov_b32_e32 v15, v2
	v_mov_b32_e32 v16, v2
	v_mov_b32_e32 v17, v2
	v_mov_b32_e32 v18, v2
	v_mov_b32_e32 v19, v2
	v_mov_b32_e32 v20, v2
	v_mov_b32_e32 v21, v2
	v_mov_b32_e32 v22, v2
	v_mov_b32_e32 v23, v2
	v_mov_b32_e32 v24, v2
	v_mov_b32_e32 v25, v2
	v_mov_b32_e32 v26, v2
	v_mov_b32_e32 v27, v2
	v_mov_b32_e32 v28, v2
	v_mov_b32_e32 v29, v2
	v_mov_b32_e32 v30, v2
	v_mov_b32_e32 v31, v2
	v_mov_b32_e32 v32, v2
	v_mov_b32_e32 v33, v2
	v_mov_b32_e32 v34, v2
	v_mov_b32_e32 v35, v2
	v_mov_b32_e32 v36, v2
	v_mov_b32_e32 v37, v2
	v_mov_b32_e32 v38, v2
	v_mov_b32_e32 v39, v2
	v_mov_b32_e32 v40, v2
	v_mov_b32_e32 v41, v2
	v_mov_b32_e32 v42, v2
	v_mov_b32_e32 v43, v2
	v_mov_b32_e32 v44, v2
	v_mov_b32_e32 v45, v2
	v_mov_b32_e32 v46, v2
	v_mov_b32_e32 v47, v2
	v_mov_b32_e32 v48, v2
	v_mov_b32_e32 v49, v2
	v_mov_b32_e32 v50, v2
	v_mov_b32_e32 v51, v2
	v_mov_b32_e32 v52, v2
	v_mov_b32_e32 v53, v2
	v_mov_b32_e32 v54, v2
	v_mov_b32_e32 v55, v2
	v_mov_b32_e32 v56, v2
	v_mov_b32_e32 v57, v2
	v_mov_b32_e32 v58, v2
	v_mov_b32_e32 v59, v2
	v_mov_b32_e32 v60, v2
	v_mov_b32_e32 v61, v2
	v_mov_b32_e32 v62, v2
	v_mov_b32_e32 v63, v2
	v_mov_b32_e32 v64, v2
	v_mov_b32_e32 v65, v2
	v_mov_b32_e32 v66, v2
	v_mov_b32_e32 v67, v2
	v_mov_b32_e32 v68, v2
	v_mov_b32_e32 v69, v2
	v_mov_b32_e32 v70, v2
	v_mov_b32_e32 v71, v2
	v_mov_b32_e32 v72, v2
	v_mov_b32_e32 v73, v2
	v_mov_b32_e32 v74, v2
	v_mov_b32_e32 v75, v2
	v_mov_b32_e32 v76, v2
	v_mov_b32_e32 v77, v2
	v_mov_b32_e32 v78, v2
	v_mov_b32_e32 v79, v2
	v_mov_b32_e32 v80, v2
	v_mov_b32_e32 v81, v2
	v_mov_b32_e32 v82, v2
	v_mov_b32_e32 v83, v2
	v_mov_b32_e32 v84, v2
	v_mov_b32_e32 v85, v2
	v_mov_b32_e32 v86, v2
	v_mov_b32_e32 v87, v2
	v_mov_b32_e32 v88, v2
	v_mov_b32_e32 v89, v2
	v_mov_b32_e32 v90, v2
	v_mov_b32_e32 v91, v2
	v_mov_b32_e32 v92, v2
	v_mov_b32_e32 v93, v2
	v_mov_b32_e32 v94, v2
	v_mov_b32_e32 v95, v2
	v_mov_b32_e32 v96, v2
	v_mov_b32_e32 v97, v2
	v_mov_b32_e32 v98, v2
	v_mov_b32_e32 v99, v2
	v_mov_b32_e32 v100, v2
	v_mov_b32_e32 v101, v2
	v_mov_b32_e32 v102, v2
	v_mov_b32_e32 v103, v2
	v_mov_b32_e32 v104, v2
	v_mov_b32_e32 v105, v2
	v_mov_b32_e32 v106, v2
	v_mov_b32_e32 v107, v2
	v_mov_b32_e32 v108, v2
	v_mov_b32_e32 v109, v2
	v_mov_b32_e32 v110, v2
	v_mov_b32_e32 v111, v2
	v_mov_b32_e32 v112, v2
	v_mov_b32_e32 v113, v2
	v_mov_b32_e32 v114, v2
	v_mov_b32_e32 v115, v2
	v_mov_b32_e32 v116, v2
	v_mov_b32_e32 v117, v2
	v_mov_b32_e32 v118, v2
	v_mov_b32_e32 v119, v2
	v_mov_b32_e32 v120, v2
	v_mov_b32_e32 v121, v2
	v_mov_b32_e32 v122, v2
	v_mov_b32_e32 v123, v2
	v_mov_b32_e32 v124, v2
	v_mov_b32_e32 v125, v2
	v_mov_b32_e32 v126, v2
	v_mov_b32_e32 v127, v2
	v_mov_b32_e32 v128, v2
	v_mov_b32_e32 v129, v2
	s_mov_b64 s[26:27], 0x8240080
	s_mov_b64 s[36:37], 0x8260080
	s_mov_b64 s[40:41], 0x8200100
	s_mov_b64 s[44:45], 0x8220100
	s_mov_b64 s[46:47], 0x8240100
	s_mov_b64 s[48:49], 0x8260100
	s_mov_b64 s[50:51], 0x8200180
	s_mov_b64 s[52:53], 0x8220180
	s_barrier

; #define GPTR(T, ptr) ((__attribute__((address_space(1))) T*)(ptr))
; template <int EPI>
; __device__ __forceinline__ void gemm_tile(const GemmArgs& g, int brow, int bcol, int parity, bool first, bool nvalid, int nbrow, int nbcol) {
;     ...
;     if (gtid_ < 256) {
;       const __attribute__((address_space(1))) f32x4* pp = GPTR(const f32x4, g.rowss + (long)(brow + gtid_) * 16);
;       ra0 = pp[0]; ra1 = pp[1]; ra2 = pp[2]; ra3 = pp[3];
;     }
; template <int EPI>
; __device__ void gemm_phase(const GemmArgs& g, int nM, int nN, int extra_items, const Params& p, int L) {
;     ...
;   for (int v = rb; v < total + extra_items; v += G) {
;     if (v < total) {
;       const int nig = 8 * nN;
;       int pm = (v / nig) * 8 + ((v % nig) & 7), pn = (v % nig) >> 3;
;       const int nv = v + G; const bool nvalid = nv < total;
;       const int npm = (nv / nig) * 8 + ((nv % nig) & 7), npn = (nv % nig) >> 3;
;       gemm_tile<EPI>(g, pm * BM, pn * BM, par++, !have, nvalid, npm * BM, npn * BM);
.LBB0_93:
	s_or_b64 exec, exec, s[0:1]
	s_add_i32 s21, s21, s30
	s_cmpk_gt_i32 s21, 0x3ff
	s_cselect_b64 s[0:1], -1, 0
	s_and_b64 vcc, exec, s[0:1]
	s_cbranch_vccnz .LBB0_76
	s_ashr_i32 s2, s21, 31
	s_lshr_b32 s2, s2, 26
	s_add_i32 s2, s21, s2
	s_and_b32 s3, s2, 0xffffffc0
	s_sub_i32 s3, s21, s3
	s_lshl_b32 s2, s2, 5
	s_lshl_b32 s12, s3, 8
	s_and_b32 s2, s2, 0xfffff800
	s_and_b32 s12, s12, 0x700
	s_lshl_b32 s3, s3, 5
	s_or_b32 s2, s12, s2
	s_and_b32 s12, s3, 0xffffff00
	s_ashr_i32 s13, s12, 31
	s_lshl_b64 s[14:15], s[12:13], 11
	s_add_u32 s14, s22, s14
	s_addc_u32 s15, s23, s15
	v_readfirstlane_b32 s3, v158
	v_lshl_add_u64 v[130:131], s[14:15], 0, v[0:1]
	s_mov_b32 m0, s3
	v_readfirstlane_b32 s3, v159
	global_load_lds_dwordx4 v[130:131], off
	s_mov_b32 m0, s3
	s_ashr_i32 s3, s2, 31
	s_lshl_b64 s[14:15], s[2:3], 11
	s_add_u32 s14, s80, s14
	s_addc_u32 s15, s81, s15
	s_bitset1_b32 s12, 7
	s_mov_b64 s[26:27], 0x20000
	s_ashr_i32 s13, s12, 31
	v_lshl_add_u64 v[130:131], v[130:131], 0, s[26:27]
	v_readfirstlane_b32 s3, v137
	s_lshl_b64 s[12:13], s[12:13], 11
	global_load_lds_dwordx4 v[130:131], off
	v_lshl_add_u64 v[130:131], s[14:15], 0, v[0:1]
	s_mov_b32 m0, s3
	v_readfirstlane_b32 s3, v136
	s_add_u32 s12, s22, s12
	global_load_lds_dwordx4 v[130:131], off
	v_lshl_add_u64 v[130:131], v[130:131], 0, s[26:27]
	s_mov_b32 m0, s3
	s_addc_u32 s13, s23, s13
	v_readfirstlane_b32 s3, v135
	global_load_lds_dwordx4 v[130:131], off
	v_lshl_add_u64 v[130:131], s[12:13], 0, v[0:1]
	s_mov_b32 m0, s3
	v_readfirstlane_b32 s3, v160
	s_bitset1_b32 s2, 7
	global_load_lds_dwordx4 v[130:131], off
	s_mov_b32 m0, s3
	s_ashr_i32 s3, s2, 31
	s_lshl_b64 s[2:3], s[2:3], 11
	s_add_u32 s2, s80, s2
	v_lshl_add_u64 v[130:131], v[130:131], 0, s[26:27]
	s_addc_u32 s3, s81, s3
	global_load_lds_dwordx4 v[130:131], off
	v_lshl_add_u64 v[130:131], s[2:3], 0, v[0:1]
	v_readfirstlane_b32 s2, v134
	s_mov_b32 m0, s2
	v_readfirstlane_b32 s2, v133
	global_load_lds_dwordx4 v[130:131], off
	v_lshl_add_u64 v[130:131], v[130:131], 0, s[26:27]
	s_mov_b32 m0, s2
	s_nop 0
	global_load_lds_dwordx4 v[130:131], off
	s_ashr_i32 s2, s21, 31
	s_lshr_b32 s2, s2, 26
	s_add_i32 s2, s21, s2
	s_and_b32 s3, s2, 0xffffffc0
	s_sub_i32 s3, s21, s3
	s_lshl_b32 s2, s2, 5
	s_lshl_b32 s12, s3, 8
	s_and_b32 s2, s2, 0xfffff800
	s_and_b32 s12, s12, 0x700
	s_lshl_b32 s3, s3, 5
	s_or_b32 s2, s12, s2
	v_mbcnt_lo_u32_b32 v248, -1, 0
	v_mbcnt_hi_u32_b32 v248, -1, v248
	v_or_b32_e32 v248, s33, v248
	s_movk_i32 s3, 0x100
	v_cmp_gt_i32_e32 vcc, s3, v248
	s_and_saveexec_b64 s[12:13], vcc
	s_cbranch_execz .Lpf_A_x
	v_add_u32_e32 v248, s2, v248
	v_mov_b32_e32 v249, 0
	v_lshlrev_b64 v[248:249], 6, v[248:249]
	v_readlane_b32 s2, v254, 62
	v_readlane_b32 s3, v254, 63
	s_nop 1
	v_lshl_add_u64 v[248:249], s[2:3], 0, v[248:249]
	global_load_dwordx4 v[232:235], v[248:249], off offset:48
	global_load_dwordx4 v[236:239], v[248:249], off offset:32
	global_load_dwordx4 v[240:243], v[248:249], off offset:16
	global_load_dwordx4 v[244:247], v[248:249], off
.Lpf_A_x:
	s_or_b64 exec, exec, s[12:13]
	s_branch .LBB0_76

; #define GPTR(T, ptr) ((__attribute__((address_space(1))) T*)(ptr))
; __device__ __forceinline__ int ptid_(int wave) { int l_; asm volatile("v_mbcnt_lo_u32_b32 %0, -1, 0\n\tv_mbcnt_hi_u32_b32 %0, -1, %0" : "=v"(l_)); return (wave << 6) | l_; }
; #define STAGE_B(P, br, kt) do { const char* _gb = (const char*)(Bt + ((long)(br) * K + (long)(kt) * BK)); \
;     __builtin_amdgcn_global_load_lds((const unsigned*)(_gb + bofl0), (unsigned*)((char*)(P) + gtid_ * 16), 16, 0, 0); \
;     __builtin_amdgcn_global_load_lds((const unsigned*)(_gb + (long)K * 128 + bofl0), (unsigned*)((char*)(P) + gtid_ * 16 + 8192), 16, 0, 0); } while (0)
; #define WAIT_V(n) asm volatile("s_waitcnt vmcnt(" #n ")" ::: "memory")
; template <int EPI>
; __device__ __forceinline__ void gemm_tile(const GemmArgs& g, int brow, int bcol, int parity, bool first, bool nvalid, int nbrow, int nbcol) {
;     ...
;   int gtid_ = ptid_(g.tid);
;   const int wid = gtid_ >> 6, lane = gtid_ & 63, wr = wid >> 2, wc = wid & 3, fr = lane & 15, fq = lane >> 4;
;   unsigned aofl0, bofl0;
;   { int _r, _c; stage_rc(gtid_ * 16, _r, _c); aofl0 = (unsigned)(_r * lda + _c) * 2u; bofl0 = (unsigned)(_r * K + _c) * 2u; }
;   f32x4 acc[2][2][4][2] = {};
;   bf16x8 At[4][2], B0[2][2], B1[2][2];
;   const int nt = K / BK;
;   float* rstd_s = (float*)(smem + 153600) + (parity & 1) * 256;
;   if (first) {
;     WAIT_V(0);
;     __syncthreads();
;     STAGE_B(SB(0, 0), bcol, 0); STAGE_A(SA(0, 0), brow, 0);
;     STAGE_B(SB(0, 1), bcol + HALF, 0); STAGE_A(SA(0, 1), brow + HALF, 0);
;   }
;   f32x4 ra0, ra1, ra2, ra3;
;   if constexpr (EPI != EPI_RES) {
;     if (gtid_ < 256) {
;       const __attribute__((address_space(1))) f32x4* pp = GPTR(const f32x4, g.rowss + (long)(brow + gtid_) * 16);
;       ra0 = pp[0]; ra1 = pp[1]; ra2 = pp[2]; ra3 = pp[3];
;     }
;   }
.LBB0_153:
	s_mov_b64 s[100:101], s[12:13]
	v_mbcnt_lo_u32_b32 v132, -1, 0
	v_mbcnt_hi_u32_b32 v132, -1, v132
	s_mul_hi_i32 s0, s18, 0x2e8ba2e9
	v_or_b32_e32 v138, s33, v132
	v_ashrrev_i32_e32 v0, 31, v138
	v_lshrrev_b32_e32 v0, 26, v0
	v_add_u32_e32 v0, v138, v0
	v_ashrrev_i32_e32 v18, 6, v0
	v_bfe_i32 v0, v138, 27, 1
	v_lshlrev_b32_e32 v142, 4, v138
	v_lshrrev_b32_e32 v0, 22, v0
	v_add_u32_e32 v0, v142, v0
	v_and_b32_e32 v0, 0xfffffc00, v0
	v_sub_u32_e32 v0, v142, v0
	s_waitcnt lgkmcnt(0)
	v_lshrrev_b32_e32 v2, 4, v0
	v_bitop3_b32 v0, v2, v0, 32 bitop3:0x6c
	v_ashrrev_i32_e32 v3, 31, v0
	s_lshr_b32 s1, s0, 31
	s_ashr_i32 s0, s0, 5
	v_lshrrev_b32_e32 v3, 26, v3
	s_add_i32 s0, s0, s1
	v_add_u32_e32 v3, v0, v3
	s_mul_i32 s1, s0, 0xb0
	v_ashrrev_i32_e32 v19, 6, v3
	v_and_b32_e32 v3, 0xc0, v3
	s_sub_i32 s34, s18, s1
	v_sub_u32_e32 v0, v0, v3
	s_lshl_b32 s2, s0, 11
	s_lshl_b32 s0, s34, 8
	v_lshlrev_b32_e32 v2, 3, v18
	v_lshlrev_b32_e32 v4, 5, v18
	v_ashrrev_i16_sdwa v0, v220, sext(v0) dst_sel:DWORD dst_unused:UNUSED_PAD src0_sel:DWORD src1_sel:BYTE_0
	s_and_b32 s3, s0, 0x700
	s_lshl_b32 s0, s34, 5
	v_and_b32_e32 v2, 0x1ffff0, v2
	v_and_b32_e32 v4, 32, v4
	v_bfe_i32 v20, v0, 0, 16
	s_and_b32 s40, s0, 0xffffff00
	v_add_u32_e32 v0, v4, v20
	v_add_lshl_u32 v2, v19, v2, 11
	v_add_u32_e32 v137, 0, v142
	v_readlane_b32 s0, v254, 7
	s_or_b32 s38, s3, s2
	v_lshl_add_u32 v0, v0, 1, v2
	s_and_b64 vcc, exec, s[12:13]
	v_add_u32_e32 v136, 0x2000, v137
	v_add_u32_e32 v135, s0, v142
	v_add_u32_e32 v134, 0x4000, v137
	v_add_u32_e32 v133, 0x6000, v137
	s_cbranch_vccnz .LBB0_155
	s_ashr_i32 s41, s40, 31
	s_lshl_b64 s[0:1], s[40:41], 11
	s_add_u32 s0, s19, s0
	s_addc_u32 s1, s21, s1
	s_add_i32 s14, 0, 0x10000
	v_add_u32_e32 v4, s14, v142
	s_waitcnt vmcnt(0)
	s_waitcnt vmcnt(0) lgkmcnt(0)
	v_readfirstlane_b32 s14, v4
	s_mov_b32 m0, s14
	v_add_u32_e32 v4, 0x2000, v4
	s_barrier
	v_lshl_add_u64 v[2:3], s[0:1], 0, v[0:1]
	global_load_lds_dwordx4 v0, s[0:1]
	v_readfirstlane_b32 s0, v4
	s_ashr_i32 s39, s38, 31
	s_mov_b64 s[26:27], 0x20000
	s_mov_b32 m0, s0
	s_lshl_b64 s[0:1], s[38:39], 11
	v_lshl_add_u64 v[2:3], v[2:3], 0, s[26:27]
	s_add_u32 s0, s80, s0
	v_readfirstlane_b32 s14, v137
	global_load_lds_dwordx4 v[2:3], off
	s_addc_u32 s1, s81, s1
	s_mov_b32 m0, s14
	v_lshl_add_u64 v[2:3], s[0:1], 0, v[0:1]
	global_load_lds_dwordx4 v0, s[0:1]
	v_readfirstlane_b32 s0, v136
	s_mov_b32 m0, s0
	s_or_b32 s0, s40, 0x80
	s_ashr_i32 s1, s0, 31
	s_lshl_b64 s[0:1], s[0:1], 11
	v_lshl_add_u64 v[2:3], v[2:3], 0, s[26:27]
	s_add_u32 s0, s19, s0
	v_readfirstlane_b32 s14, v135
	global_load_lds_dwordx4 v[2:3], off
	s_addc_u32 s1, s21, s1
	s_mov_b32 m0, s14
	v_add_u32_e32 v4, 0x2000, v135
	v_lshl_add_u64 v[2:3], s[0:1], 0, v[0:1]
	global_load_lds_dwordx4 v0, s[0:1]
	v_readfirstlane_b32 s0, v4
	s_mov_b32 m0, s0
	s_or_b32 s0, s38, 0x80
	s_ashr_i32 s1, s0, 31
	s_lshl_b64 s[0:1], s[0:1], 11
	v_lshl_add_u64 v[2:3], v[2:3], 0, s[26:27]
	s_add_u32 s0, s80, s0
	v_readfirstlane_b32 s14, v134
	global_load_lds_dwordx4 v[2:3], off
	s_addc_u32 s1, s81, s1
	s_mov_b32 m0, s14
	v_lshl_add_u64 v[2:3], s[0:1], 0, v[0:1]
	global_load_lds_dwordx4 v0, s[0:1]
	v_readfirstlane_b32 s0, v133
	v_lshl_add_u64 v[2:3], v[2:3], 0, s[26:27]
	s_mov_b32 m0, s0
	s_nop 0
	global_load_lds_dwordx4 v[2:3], off
.LBB0_155:
	s_movk_i32 s0, 0x100
	v_cmp_gt_i32_e64 s[0:1], s0, v138
	s_mov_b64 vcc, s[100:101]
	s_cbranch_vccnz .Lhp_C_1
	s_and_saveexec_b64 s[14:15], s[0:1]
	s_cbranch_execz .LBB0_157
	v_add_u32_e32 v2, s38, v138
	v_ashrrev_i32_e32 v3, 31, v2
	v_lshlrev_b64 v[2:3], 6, v[2:3]
	v_lshl_add_u64 v[14:15], s[36:37], 0, v[2:3]
	global_load_dwordx4 v[2:5], v[14:15], off offset:48
	global_load_dwordx4 v[6:9], v[14:15], off offset:32
	global_load_dwordx4 v[10:13], v[14:15], off offset:16
	s_nop 0
	global_load_dwordx4 v[14:17], v[14:15], off

; #define BAR __builtin_amdgcn_s_barrier()
; template <int EPI>
; __device__ __forceinline__ void gemm_tile(const GemmArgs& g, int brow, int bcol, int parity, bool first, bool nvalid, int nbrow, int nbcol) {
;     ...
;   if (wr == 1) BAR;
.Lhp_C_1:
	v_ashrrev_i32_e32 v21, 8, v138
	v_cmp_eq_u32_e32 vcc, 1, v21
	s_and_saveexec_b64 s[14:15], vcc
	s_cbranch_execz .LBB0_159
	s_barrier

; __device__ __forceinline__ float frsq(float x) { return __builtin_amdgcn_rsqf(x); }
; #define WAIT_V(n) asm volatile("s_waitcnt vmcnt(" #n ")" ::: "memory")
; #define BAR __builtin_amdgcn_s_barrier()
; template <int EPI>
; __device__ __forceinline__ void gemm_tile(const GemmArgs& g, int brow, int bcol, int parity, bool first, bool nvalid, int nbrow, int nbcol) {
;     ...
;   if (first) { WAIT_V(4); } else { WAIT_V(0); }
;   BAR;
;   if constexpr (EPI != EPI_RES) {
;     if (gtid_ < 256) {
;       float s = ((ra0[0] + ra0[1]) + (ra0[2] + ra0[3])) + ((ra1[0] + ra1[1]) + (ra1[2] + ra1[3])) + ((ra2[0] + ra2[1]) + (ra2[2] + ra2[3])) + ((ra3[0] + ra3[1]) + (ra3[2] + ra3[3]));
;       rstd_s[gtid_] = frsq(s * (1.0f / 1024.0f) + 1e-6f);
.LBB0_161:
	s_andn2_b64 vcc, exec, s[12:13]
	s_cbranch_vccnz .LBB0_163
	s_waitcnt vmcnt(8)
.LBB0_163:
	s_lshl_b32 s12, s24, 10
	s_and_b32 s12, s12, 0x400
	s_add_i32 s14, s12, 0
	s_add_i32 s14, s14, 0x25800
	s_barrier
	s_and_saveexec_b64 s[12:13], s[0:1]
	s_cbranch_execz .LBB0_165
	s_mov_b64 vcc, s[100:101]
	s_cbranch_vccz .Lhp_C_2
	v_mov_b32_e32 v2, v232
	v_mov_b32_e32 v3, v233
	v_mov_b32_e32 v4, v234
	v_mov_b32_e32 v5, v235
	v_mov_b32_e32 v6, v236
	v_mov_b32_e32 v7, v237
	v_mov_b32_e32 v8, v238
	v_mov_b32_e32 v9, v239
	v_mov_b32_e32 v10, v240
	v_mov_b32_e32 v11, v241
	v_mov_b32_e32 v12, v242
	v_mov_b32_e32 v13, v243
	v_mov_b32_e32 v14, v244
	v_mov_b32_e32 v15, v245
	v_mov_b32_e32 v16, v246
	v_mov_b32_e32 v17, v247
	s_branch .Lhp_C_3

; __device__ __forceinline__ float frsq(float x) { return __builtin_amdgcn_rsqf(x); }
; #define STAGE_B(P, br, kt) do { const char* _gb = (const char*)(Bt + ((long)(br) * K + (long)(kt) * BK)); \
;     __builtin_amdgcn_global_load_lds((const unsigned*)(_gb + bofl0), (unsigned*)((char*)(P) + gtid_ * 16), 16, 0, 0); \
;     __builtin_amdgcn_global_load_lds((const unsigned*)(_gb + (long)K * 128 + bofl0), (unsigned*)((char*)(P) + gtid_ * 16 + 8192), 16, 0, 0); } while (0)
; template <int EPI>
; __device__ __forceinline__ void gemm_tile(const GemmArgs& g, int brow, int bcol, int parity, bool first, bool nvalid, int nbrow, int nbcol) {
;     ...
;       float s = ((ra0[0] + ra0[1]) + (ra0[2] + ra0[3])) + ((ra1[0] + ra1[1]) + (ra1[2] + ra1[3])) + ((ra2[0] + ra2[1]) + (ra2[2] + ra2[3])) + ((ra3[0] + ra3[1]) + (ra3[2] + ra3[3]));
;       rstd_s[gtid_] = frsq(s * (1.0f / 1024.0f) + 1e-6f);
;     }
;   }
;   STAGE_B(SB(1, 0), bcol, 1); STAGE_A(SA(1, 0), brow, 1); STAGE_B(SB(1, 1), bcol + HALF, 1);
.Lhp_C_3:
	v_mov_b32_e32 v22, v15
	v_mov_b32_e32 v23, v16
	v_mov_b32_e32 v15, v17
	v_mov_b32_e32 v16, v11
	v_mov_b32_e32 v17, v12
	v_mov_b32_e32 v11, v13
	v_pk_add_f32 v[14:15], v[22:23], v[14:15]
	v_pk_add_f32 v[10:11], v[16:17], v[10:11]
	v_pk_add_f32 v[14:15], v[14:15], v[14:15] op_sel_hi:[0,1]
	v_pk_add_f32 v[10:11], v[10:11], v[10:11] op_sel_hi:[0,1]
	v_add_f32_e32 v7, v6, v7
	v_add_f32_e32 v9, v8, v9
	v_mov_b32_e32 v6, v2
	v_mov_b32_e32 v8, v3
	v_mov_b32_e32 v10, v4
	v_mov_b32_e32 v14, v5
	v_pk_add_f32 v[2:3], v[6:7], v[8:9]
	v_pk_add_f32 v[4:5], v[10:11], v[14:15]
	s_nop 0
	v_pk_add_f32 v[2:3], v[2:3], v[4:5]
	s_nop 0
	v_add_f32_e32 v2, v2, v3
	v_fmamk_f32 v2, v2, 0x3a800000, v201
	v_rsq_f32_e32 v2, v2
	v_lshl_add_u32 v3, v138, 2, s14
	ds_write_b32 v3, v2
.LBB0_165:
	s_or_b64 exec, exec, s[12:13]
	s_ashr_i32 s41, s40, 31
	s_lshl_b64 s[12:13], s[40:41], 11
	s_add_u32 s0, s19, s12
	v_readlane_b32 s25, v254, 8
	s_addc_u32 s1, s21, s13
	s_mov_b64 vcc, s[100:101]
	s_cbranch_vccz .Lhp_C_4
	s_waitcnt vmcnt(8)
	s_branch .Lhp_C_5

; #define STAGE_B(P, br, kt) do { const char* _gb = (const char*)(Bt + ((long)(br) * K + (long)(kt) * BK)); \
;     __builtin_amdgcn_global_load_lds((const unsigned*)(_gb + bofl0), (unsigned*)((char*)(P) + gtid_ * 16), 16, 0, 0); \
;     __builtin_amdgcn_global_load_lds((const unsigned*)(_gb + (long)K * 128 + bofl0), (unsigned*)((char*)(P) + gtid_ * 16 + 8192), 16, 0, 0); } while (0)
; #define WAIT_V(n) asm volatile("s_waitcnt vmcnt(" #n ")" ::: "memory")
; #define BAR __builtin_amdgcn_s_barrier()
; template <int EPI>
; __device__ __forceinline__ void gemm_tile(const GemmArgs& g, int brow, int bcol, int parity, bool first, bool nvalid, int nbrow, int nbcol) {
;     ...
;   STAGE_B(SB(1, 0), bcol, 1); STAGE_A(SA(1, 0), brow, 1); STAGE_B(SB(1, 1), bcol + HALF, 1);
;   WAIT_V(6); BAR;
.Lhp_C_5:
	v_lshl_add_u64 v[2:3], s[0:1], 0, v[0:1]
	v_add_u32_e32 v150, s25, v142
	s_mov_b64 s[26:27], 0x80
	v_readfirstlane_b32 s0, v150
	v_add_u32_e32 v151, 0x2000, v150
	v_lshl_add_u64 v[4:5], v[2:3], 0, s[26:27]
	s_mov_b32 m0, s0
	v_readfirstlane_b32 s0, v151
	s_ashr_i32 s39, s38, 31
	global_load_lds_dwordx4 v[4:5], off
	s_mov_b32 m0, s0
	s_lshl_b64 s[0:1], s[38:39], 11
	s_mov_b64 s[42:43], 0x20080
	s_add_u32 s0, s80, s0
	v_lshl_add_u64 v[2:3], v[2:3], 0, s[42:43]
	s_addc_u32 s1, s81, s1
	v_add_u32_e32 v152, 0x8000, v137
	global_load_lds_dwordx4 v[2:3], off
	v_lshl_add_u64 v[2:3], s[0:1], 0, v[0:1]
	v_readfirstlane_b32 s0, v152
	v_add_u32_e32 v153, 0xa000, v137
	v_lshl_add_u64 v[4:5], v[2:3], 0, s[26:27]
	s_mov_b32 m0, s0
	v_readfirstlane_b32 s0, v153
	global_load_lds_dwordx4 v[4:5], off
	s_mov_b32 m0, s0
	s_or_b32 s0, s40, 0x80
	s_ashr_i32 s1, s0, 31
	s_lshl_b64 s[0:1], s[0:1], 11
	s_add_u32 s0, s19, s0
	v_lshl_add_u64 v[2:3], v[2:3], 0, s[42:43]
	s_addc_u32 s1, s21, s1
	global_load_lds_dwordx4 v[2:3], off
	v_lshl_add_u64 v[2:3], s[0:1], 0, v[0:1]
	v_readlane_b32 s1, v254, 9
	v_lshl_add_u64 v[4:5], v[2:3], 0, s[26:27]
	v_lshl_add_u64 v[2:3], v[2:3], 0, s[42:43]
	v_add_u32_e32 v155, s1, v142
	v_add_u32_e32 v156, 0x2000, v155
	v_readfirstlane_b32 s0, v155
	s_mov_b32 m0, s0
	v_readfirstlane_b32 s0, v156
	global_load_lds_dwordx4 v[4:5], off
	s_mov_b32 m0, s0
	v_and_b32_e32 v139, 15, v132
	global_load_lds_dwordx4 v[2:3], off
	v_lshlrev_b32_e32 v5, 2, v132
	v_and_b32_e32 v2, 48, v132
	v_lshlrev_b32_e32 v4, 6, v139
	v_and_b32_e32 v5, 32, v5
	v_bitop3_b32 v4, v4, v5, v2 bitop3:0x36
	v_readlane_b32 s0, v254, 7
	v_lshlrev_b32_e32 v11, 6, v132
	v_add_u32_e32 v9, s1, v4
	v_add_u32_e32 v7, s0, v4
	s_movk_i32 s0, 0x3c0
	v_and_or_b32 v2, v11, s0, v2
	s_add_i32 s0, s2, s3
	v_xad_u32 v5, v2, v5, 0
	v_lshlrev_b32_e32 v2, 14, v18
	s_ashr_i32 s1, s0, 31
	s_add_i32 s15, 0, 0x10000
	v_and_b32_e32 v2, 0xffff8000, v2
	s_lshl_b64 s[0:1], s[0:1], 11
	v_ashrrev_i32_e32 v140, 6, v138
	v_lshl_add_u32 v2, v19, 11, v2
	v_and_b32_e32 v14, 1, v18
	s_add_u32 s0, s10, s0
	v_and_b32_e32 v141, 3, v140
	s_mov_b64 vcc, s[100:101]
	s_cbranch_vccz .Lhp_C_6
	s_waitcnt vmcnt(14)
	s_branch .Lhp_C_7

; #define GPTR(T, ptr) ((__attribute__((address_space(1))) T*)(ptr))
; __device__ __forceinline__ float frsq(float x) { return __builtin_amdgcn_rsqf(x); }
; #define STAGE_B(P, br, kt) do { const char* _gb = (const char*)(Bt + ((long)(br) * K + (long)(kt) * BK)); \
;     __builtin_amdgcn_global_load_lds((const unsigned*)(_gb + bofl0), (unsigned*)((char*)(P) + gtid_ * 16), 16, 0, 0); \
;     __builtin_amdgcn_global_load_lds((const unsigned*)(_gb + (long)K * 128 + bofl0), (unsigned*)((char*)(P) + gtid_ * 16 + 8192), 16, 0, 0); } while (0)
; #define WAIT_V(n) asm volatile("s_waitcnt vmcnt(" #n ")" ::: "memory")
; #define BAR __builtin_amdgcn_s_barrier()
; template <int EPI>
; __device__ __forceinline__ void gemm_tile(const GemmArgs& g, int brow, int bcol, int parity, bool first, bool nvalid, int nbrow, int nbcol) {
;     ...
;   f32x4 acc[2][2][4][2] = {};
;   bf16x8 At[4][2], B0[2][2], B1[2][2];
;   const int nt = K / BK;
;   float* rstd_s = (float*)(smem + 153600) + (parity & 1) * 256;
;   if (first) {
;     WAIT_V(0);
;     __syncthreads();
;     STAGE_B(SB(0, 0), bcol, 0); STAGE_A(SA(0, 0), brow, 0);
;     STAGE_B(SB(0, 1), bcol + HALF, 0); STAGE_A(SA(0, 1), brow + HALF, 0);
;   }
;   f32x4 ra0, ra1, ra2, ra3;
;   if constexpr (EPI != EPI_RES) {
;     if (gtid_ < 256) {
;       const __attribute__((address_space(1))) f32x4* pp = GPTR(const f32x4, g.rowss + (long)(brow + gtid_) * 16);
;       ra0 = pp[0]; ra1 = pp[1]; ra2 = pp[2]; ra3 = pp[3];
;     }
;   }
;   if (wr == 1) BAR;
;   if (first) { WAIT_V(4); } else { WAIT_V(0); }
;   BAR;
;   if constexpr (EPI != EPI_RES) {
;     if (gtid_ < 256) {
;       float s = ((ra0[0] + ra0[1]) + (ra0[2] + ra0[3])) + ((ra1[0] + ra1[1]) + (ra1[2] + ra1[3])) + ((ra2[0] + ra2[1]) + (ra2[2] + ra2[3])) + ((ra3[0] + ra3[1]) + (ra3[2] + ra3[3]));
;       rstd_s[gtid_] = frsq(s * (1.0f / 1024.0f) + 1e-6f);
;     }
;   }
;   STAGE_B(SB(1, 0), bcol, 1); STAGE_A(SA(1, 0), brow, 1); STAGE_B(SB(1, 1), bcol + HALF, 1);
;   WAIT_V(6); BAR;
.Lhp_C_7:
	v_lshlrev_b32_e32 v10, 13, v21
	v_lshl_or_b32 v2, v14, 6, v2
	s_addc_u32 s1, s11, s1
	v_lshlrev_b32_e32 v3, 12, v141
	v_add_u32_e32 v6, s15, v4
	v_add_u32_e32 v8, s25, v4
	v_add_u32_e32 v4, 0, v4
	v_or_b32_e32 v11, 0x800, v10
	v_or_b32_e32 v12, 0x1000, v10
	v_or_b32_e32 v13, 0x1800, v10
	v_lshl_add_u32 v130, v20, 1, v2
	s_add_u32 s12, s22, s12
	v_mov_b32_e32 v2, 0
	v_lshlrev_b32_e32 v143, 6, v21
	v_mov_b32_e32 v131, v1
	s_addc_u32 s13, s23, s13
	s_mov_b32 s25, -2
	v_add_u32_e32 v157, v6, v3
	v_add_u32_e32 v147, v4, v10
	v_add_u32_e32 v146, v5, v11
	v_add_u32_e32 v145, v5, v12
	v_add_u32_e32 v144, v5, v13
	v_add_u32_e32 v154, v7, v3
	v_add_u32_e32 v149, v8, v3
	v_add_u32_e32 v148, v9, v3
	v_mov_b32_e32 v3, v2
	v_mov_b32_e32 v4, v2
	v_mov_b32_e32 v5, v2
	v_mov_b32_e32 v6, v2
	v_mov_b32_e32 v7, v2
	v_mov_b32_e32 v8, v2
	v_mov_b32_e32 v9, v2
	v_mov_b32_e32 v10, v2
	v_mov_b32_e32 v11, v2
	v_mov_b32_e32 v12, v2
	v_mov_b32_e32 v13, v2
	v_mov_b32_e32 v14, v2
	v_mov_b32_e32 v15, v2
	v_mov_b32_e32 v16, v2
	v_mov_b32_e32 v17, v2
	v_mov_b32_e32 v18, v2
	v_mov_b32_e32 v19, v2
	v_mov_b32_e32 v20, v2
	v_mov_b32_e32 v21, v2
	v_mov_b32_e32 v22, v2
	v_mov_b32_e32 v23, v2
	v_mov_b32_e32 v24, v2
	v_mov_b32_e32 v25, v2
	v_mov_b32_e32 v26, v2
	v_mov_b32_e32 v27, v2
	v_mov_b32_e32 v28, v2
	v_mov_b32_e32 v29, v2
	v_mov_b32_e32 v30, v2
	v_mov_b32_e32 v31, v2
	v_mov_b32_e32 v32, v2
	v_mov_b32_e32 v33, v2
	v_mov_b32_e32 v34, v2
	v_mov_b32_e32 v35, v2
	v_mov_b32_e32 v36, v2
	v_mov_b32_e32 v37, v2
	v_mov_b32_e32 v38, v2
	v_mov_b32_e32 v39, v2
	v_mov_b32_e32 v40, v2
	v_mov_b32_e32 v41, v2
	v_mov_b32_e32 v42, v2
	v_mov_b32_e32 v43, v2
	v_mov_b32_e32 v44, v2
	v_mov_b32_e32 v45, v2
	v_mov_b32_e32 v46, v2
	v_mov_b32_e32 v47, v2
	v_mov_b32_e32 v48, v2
	v_mov_b32_e32 v49, v2
	v_mov_b32_e32 v50, v2
	v_mov_b32_e32 v51, v2
	v_mov_b32_e32 v52, v2
	v_mov_b32_e32 v53, v2
	v_mov_b32_e32 v54, v2
	v_mov_b32_e32 v55, v2
	v_mov_b32_e32 v56, v2
	v_mov_b32_e32 v57, v2
	v_mov_b32_e32 v58, v2
	v_mov_b32_e32 v59, v2
	v_mov_b32_e32 v60, v2
	v_mov_b32_e32 v61, v2
	v_mov_b32_e32 v62, v2
	v_mov_b32_e32 v63, v2
	v_mov_b32_e32 v64, v2
	v_mov_b32_e32 v65, v2
	v_mov_b32_e32 v66, v2
	v_mov_b32_e32 v67, v2
	v_mov_b32_e32 v68, v2
	v_mov_b32_e32 v69, v2
	v_mov_b32_e32 v70, v2
	v_mov_b32_e32 v71, v2
	v_mov_b32_e32 v72, v2
	v_mov_b32_e32 v73, v2
	v_mov_b32_e32 v74, v2
	v_mov_b32_e32 v75, v2
	v_mov_b32_e32 v76, v2
	v_mov_b32_e32 v77, v2
	v_mov_b32_e32 v78, v2
	v_mov_b32_e32 v79, v2
	v_mov_b32_e32 v80, v2
	v_mov_b32_e32 v81, v2
	v_mov_b32_e32 v82, v2
	v_mov_b32_e32 v83, v2
	v_mov_b32_e32 v84, v2
	v_mov_b32_e32 v85, v2
	v_mov_b32_e32 v86, v2
	v_mov_b32_e32 v87, v2
	v_mov_b32_e32 v88, v2
	v_mov_b32_e32 v89, v2
	v_mov_b32_e32 v90, v2
	v_mov_b32_e32 v91, v2
	v_mov_b32_e32 v92, v2
	v_mov_b32_e32 v93, v2
	v_mov_b32_e32 v94, v2
	v_mov_b32_e32 v95, v2
	v_mov_b32_e32 v96, v2
	v_mov_b32_e32 v97, v2
	v_mov_b32_e32 v98, v2
	v_mov_b32_e32 v99, v2
	v_mov_b32_e32 v100, v2
	v_mov_b32_e32 v101, v2
	v_mov_b32_e32 v102, v2
	v_mov_b32_e32 v103, v2
	v_mov_b32_e32 v104, v2
	v_mov_b32_e32 v105, v2
	v_mov_b32_e32 v106, v2
	v_mov_b32_e32 v107, v2
	v_mov_b32_e32 v108, v2
	v_mov_b32_e32 v109, v2
	v_mov_b32_e32 v110, v2
	v_mov_b32_e32 v111, v2
	v_mov_b32_e32 v112, v2
	v_mov_b32_e32 v113, v2
	v_mov_b32_e32 v114, v2
	v_mov_b32_e32 v115, v2
	v_mov_b32_e32 v116, v2
	v_mov_b32_e32 v117, v2
	v_mov_b32_e32 v118, v2
	v_mov_b32_e32 v119, v2
	v_mov_b32_e32 v120, v2
	v_mov_b32_e32 v121, v2
	v_mov_b32_e32 v122, v2
	v_mov_b32_e32 v123, v2
	v_mov_b32_e32 v124, v2
	v_mov_b32_e32 v125, v2
	v_mov_b32_e32 v126, v2
	v_mov_b32_e32 v127, v2
	v_mov_b32_e32 v128, v2
	v_mov_b32_e32 v129, v2
	s_mov_b64 s[26:27], 0x8240080
	s_mov_b64 s[42:43], 0x8260080
	s_mov_b64 s[44:45], 0x8200100
	s_mov_b64 s[46:47], 0x8220100
	s_mov_b64 s[48:49], 0x8240100
	s_mov_b64 s[50:51], 0x8260100
	s_mov_b64 s[52:53], 0x8200180
	s_mov_b64 s[56:57], 0x8220180
	s_mov_b64 s[66:67], 0x20100
	s_mov_b64 s[76:77], 0x40100
	s_mov_b64 s[96:97], 0x60100
	s_mov_b64 vcc, 0x20180
	s_mov_b64 s[60:61], 0x40180
	s_mov_b64 s[94:95], 0x60180
	s_barrier

; #define GPTR(T, ptr) ((__attribute__((address_space(1))) T*)(ptr))
; template <int EPI>
; __device__ __forceinline__ void gemm_tile(const GemmArgs& g, int brow, int bcol, int parity, bool first, bool nvalid, int nbrow, int nbcol) {
;     ...
;     if (gtid_ < 256) {
;       const __attribute__((address_space(1))) f32x4* pp = GPTR(const f32x4, g.rowss + (long)(brow + gtid_) * 16);
;       ra0 = pp[0]; ra1 = pp[1]; ra2 = pp[2]; ra3 = pp[3];
;     }
; template <int EPI>
; __device__ void gemm_phase(const GemmArgs& g, int nM, int nN, int extra_items, const Params& p, int L) {
;     ...
;   for (int v = rb; v < total + extra_items; v += G) {
;     if (v < total) {
;       const int nig = 8 * nN;
;       int pm = (v / nig) * 8 + ((v % nig) & 7), pn = (v % nig) >> 3;
;       const int nv = v + G; const bool nvalid = nv < total;
;       const int npm = (nv / nig) * 8 + ((nv % nig) & 7), npn = (nv % nig) >> 3;
;       gemm_tile<EPI>(g, pm * BM, pn * BM, par++, !have, nvalid, npm * BM, npn * BM);
.LBB0_169:
	s_or_b64 exec, exec, s[0:1]
	s_add_i32 s18, s18, s30
	s_cmpk_gt_i32 s18, 0xaff
	s_cselect_b64 s[0:1], -1, 0
	s_and_b64 vcc, exec, s[0:1]
	s_cbranch_vccnz .LBB0_152
	s_mul_hi_i32 s2, s18, 0x2e8ba2e9
	s_lshr_b32 s3, s2, 31
	s_ashr_i32 s2, s2, 5
	s_add_i32 s2, s2, s3
	s_mul_i32 s3, s2, 0xb0
	s_sub_i32 s3, s18, s3
	s_lshl_b32 s12, s3, 8
	s_lshl_b32 s2, s2, 11
	s_and_b32 s12, s12, 0x700
	s_lshl_b32 s3, s3, 5
	s_or_b32 s2, s12, s2
	s_and_b32 s12, s3, 0xffffff00
	s_ashr_i32 s13, s12, 31
	s_lshl_b64 s[26:27], s[12:13], 11
	s_add_u32 s26, s19, s26
	s_addc_u32 s27, s21, s27
	v_readfirstlane_b32 s3, v158
	v_lshl_add_u64 v[130:131], s[26:27], 0, v[0:1]
	s_mov_b32 m0, s3
	v_readfirstlane_b32 s3, v159
	global_load_lds_dwordx4 v[130:131], off
	s_mov_b32 m0, s3
	s_ashr_i32 s3, s2, 31
	s_lshl_b64 s[26:27], s[2:3], 11
	s_add_u32 s26, s80, s26
	s_addc_u32 s27, s81, s27
	s_bitset1_b32 s12, 7
	s_mov_b64 s[42:43], 0x20000
	s_ashr_i32 s13, s12, 31
	v_lshl_add_u64 v[130:131], v[130:131], 0, s[42:43]
	v_readfirstlane_b32 s3, v137
	s_lshl_b64 s[12:13], s[12:13], 11
	global_load_lds_dwordx4 v[130:131], off
	v_lshl_add_u64 v[130:131], s[26:27], 0, v[0:1]
	s_mov_b32 m0, s3
	v_readfirstlane_b32 s3, v136
	s_add_u32 s12, s19, s12
	global_load_lds_dwordx4 v[130:131], off
	v_lshl_add_u64 v[130:131], v[130:131], 0, s[42:43]
	s_mov_b32 m0, s3
	s_addc_u32 s13, s21, s13
	v_readfirstlane_b32 s3, v135
	global_load_lds_dwordx4 v[130:131], off
	v_lshl_add_u64 v[130:131], s[12:13], 0, v[0:1]
	s_mov_b32 m0, s3
	v_readfirstlane_b32 s3, v160
	s_bitset1_b32 s2, 7
	global_load_lds_dwordx4 v[130:131], off
	s_mov_b32 m0, s3
	s_ashr_i32 s3, s2, 31
	s_lshl_b64 s[2:3], s[2:3], 11
	s_add_u32 s2, s80, s2
	v_lshl_add_u64 v[130:131], v[130:131], 0, s[42:43]
	s_addc_u32 s3, s81, s3
	global_load_lds_dwordx4 v[130:131], off
	v_lshl_add_u64 v[130:131], s[2:3], 0, v[0:1]
	v_readfirstlane_b32 s2, v134
	s_mov_b32 m0, s2
	v_readfirstlane_b32 s2, v133
	global_load_lds_dwordx4 v[130:131], off
	v_lshl_add_u64 v[130:131], v[130:131], 0, s[42:43]
	s_mov_b32 m0, s2
	s_nop 0
	global_load_lds_dwordx4 v[130:131], off
	s_mul_hi_i32 s2, s18, 0x2e8ba2e9
	s_lshr_b32 s3, s2, 31
	s_ashr_i32 s2, s2, 5
	s_add_i32 s2, s2, s3
	s_mul_i32 s3, s2, 0xb0
	s_sub_i32 s3, s18, s3
	s_lshl_b32 s12, s3, 8
	s_lshl_b32 s2, s2, 11
	s_and_b32 s12, s12, 0x700
	s_lshl_b32 s3, s3, 5
	s_or_b32 s2, s12, s2
	v_mbcnt_lo_u32_b32 v248, -1, 0
	v_mbcnt_hi_u32_b32 v248, -1, v248
	v_or_b32_e32 v248, s33, v248
	s_movk_i32 s3, 0x100
	v_cmp_gt_i32_e32 vcc, s3, v248
	s_and_saveexec_b64 s[12:13], vcc
	s_cbranch_execz .Lpf_C_x
	v_add_u32_e32 v248, s2, v248
	v_mov_b32_e32 v249, 0
	v_lshlrev_b64 v[248:249], 6, v[248:249]
	v_lshl_add_u64 v[248:249], s[36:37], 0, v[248:249]
	global_load_dwordx4 v[232:235], v[248:249], off offset:48
	global_load_dwordx4 v[236:239], v[248:249], off offset:32
	global_load_dwordx4 v[240:243], v[248:249], off offset:16
	global_load_dwordx4 v[244:247], v[248:249], off
